# B3 row loops rewritten: lane = (row, 4 channels), 16-byte loads / 8-byte stores, 16-lane DPP groupnorm sums, three groups in flight
# speedup vs baseline: 1.0000x; 1.0000x over previous
.LBB0_142:
	v_lshrrev_b32_e32 v170, 6, v133
	v_bfe_u32 v171, v133, 4, 2
	v_and_b32_e32 v173, 15, v133
	v_lshlrev_b32_e32 v173, 2, v173
	v_lshl_add_u32 v173, v170, 6, v173
	v_lshlrev_b32_e32 v172, 4, v170
	v_lshl_add_u32 v172, v171, 7, v172
	v_add_u32_e32 v172, 0x19110000, v172
	v_lshlrev_b32_e32 v174, 2, v173
	v_lshl_add_u32 v174, v171, 11, v174
	v_add_u32_e32 v174, 0x19314000, v174
	v_mul_u32_u24_e32 v175, 0x1900, v171
	v_lshl_add_u32 v175, v173, 1, v175
	v_add_u32_e32 v175, 0x6a01100, v175
	v_lshlrev_b32_e32 v176, 1, v173
	v_lshl_add_u32 v176, v171, 11, v176
	v_add_u32_e32 v176, 0x4580200, v176
	v_mul_u32_u24_e32 v177, 0x300000, v170
	v_mul_u32_u24_e32 v178, 0x600, v171
	v_add_u32_e32 v177, v177, v178
	v_and_b32_e32 v178, 15, v133
	v_lshl_add_u32 v177, v178, 4, v177
	v_add_u32_e32 v177, 0xcf90500, v177
	v_readlane_b32 s0, v215, 36
	v_readlane_b32 s1, v215, 37
	s_lshl_b32 s2, s76, 9
	v_add_u32_e32 v178, s2, v173
	v_lshlrev_b32_e32 v178, 2, v178
	s_nop 1
	global_load_dwordx4 v[160:163], v178, s[0:1]
	v_readlane_b32 s0, v215, 38
	v_readlane_b32 s1, v215, 39
	s_mov_b32 vcc_hi, 0x7060302
	s_nop 3
	global_load_dwordx4 v[164:167], v178, s[0:1]
	v_readlane_b32 s21, v212, 7
	s_waitcnt vmcnt(0)
	s_lshl_b32 s1, s24, 7
	v_add_u32_e32 v169, s1, v172
	global_load_dwordx4 v[100:103], v169, s[94:95]
	s_lshr_b32 s1, s24, 11
	s_mul_i32 s1, s1, 0x1800000
	s_and_b32 s2, s24, 0x7ff
	s_mul_i32 s2, s2, 0x600
	s_add_i32 s1, s1, s2
	v_add_u32_e32 v169, s1, v177
	global_load_dwordx4 v[104:107], v169, s[94:95]
	s_lshl_b32 s1, s24, 11
	v_add_u32_e32 v169, s1, v174
	global_load_dwordx4 v[108:111], v169, s[94:95]
	s_mul_i32 s1, s24, 0x1900
	v_add_u32_e32 v169, s1, v175
	global_load_dwordx2 v[112:113], v169, s[94:95]
	s_add_i32 vcc_lo, s24, s21
	s_cmpk_gt_i32 vcc_lo, 0x3fff
	s_cbranch_scc1 .Lb3w_last0
	s_lshl_b32 s1, vcc_lo, 7
	v_add_u32_e32 v169, s1, v172
	global_load_dwordx4 v[114:117], v169, s[94:95]
	s_lshr_b32 s1, vcc_lo, 11
	s_mul_i32 s1, s1, 0x1800000
	s_and_b32 s2, vcc_lo, 0x7ff
	s_mul_i32 s2, s2, 0x600
	s_add_i32 s1, s1, s2
	v_add_u32_e32 v169, s1, v177
	global_load_dwordx4 v[118:121], v169, s[94:95]
	s_lshl_b32 s1, vcc_lo, 11
	v_add_u32_e32 v169, s1, v174
	global_load_dwordx4 v[122:125], v169, s[94:95]
	s_mul_i32 s1, vcc_lo, 0x1900
	v_add_u32_e32 v169, s1, v175
	global_load_dwordx2 v[126:127], v169, s[94:95]
.Lb3w_loop:
	s_add_i32 vcc_lo, s24, s21
	s_add_i32 vcc_lo, vcc_lo, s21
	s_cmpk_gt_i32 vcc_lo, 0x3fff
	s_cbranch_scc1 .Lb3w_tail0
	s_lshl_b32 s1, vcc_lo, 7
	v_add_u32_e32 v169, s1, v172
	global_load_dwordx4 v[134:137], v169, s[94:95]
	s_lshr_b32 s1, vcc_lo, 11
	s_mul_i32 s1, s1, 0x1800000
	s_and_b32 s2, vcc_lo, 0x7ff
	s_mul_i32 s2, s2, 0x600
	s_add_i32 s1, s1, s2
	v_add_u32_e32 v169, s1, v177
	global_load_dwordx4 v[138:141], v169, s[94:95]
	s_lshl_b32 s1, vcc_lo, 11
	v_add_u32_e32 v169, s1, v174
	global_load_dwordx4 v[142:145], v169, s[94:95]
	s_mul_i32 s1, vcc_lo, 0x1900
	v_add_u32_e32 v169, s1, v175
	global_load_dwordx2 v[146:147], v169, s[94:95]
	s_waitcnt vmcnt(8)
	v_fmac_f32_e32 v108, v102, v104
	v_fmac_f32_e32 v109, v102, v105
	v_fmac_f32_e32 v110, v102, v106
	v_fmac_f32_e32 v111, v102, v107
	v_add_f32_e32 v148, v108, v109
	v_add_f32_e32 v149, v110, v111
	v_lshlrev_b32_e32 v150, 16, v112
	v_add_f32_e32 v148, v148, v149
	v_and_b32_e32 v151, 0xffff0000, v112
	v_lshlrev_b32_e32 v152, 16, v113
	v_add_f32_dpp v148, v148, v148 quad_perm:[1,0,3,2] row_mask:0xf bank_mask:0xf bound_ctrl:1
	v_and_b32_e32 v153, 0xffff0000, v113
	v_mul_f32_e32 v154, 0xbfb8aa3b, v150
	v_add_f32_dpp v148, v148, v148 quad_perm:[2,3,0,1] row_mask:0xf bank_mask:0xf bound_ctrl:1
	v_mul_f32_e32 v155, 0xbfb8aa3b, v151
	v_mul_f32_e32 v156, 0xbfb8aa3b, v152
	v_add_f32_dpp v148, v148, v148 row_half_mirror row_mask:0xf bank_mask:0xf bound_ctrl:1
	v_mul_f32_e32 v157, 0xbfb8aa3b, v153
	v_exp_f32_e32 v154, v154
	v_add_f32_dpp v148, v148, v148 row_mirror row_mask:0xf bank_mask:0xf bound_ctrl:1
	v_exp_f32_e32 v155, v155
	v_exp_f32_e32 v156, v156
	v_fmac_f32_e32 v108, v148, v193
	v_fmac_f32_e32 v109, v148, v193
	v_fmac_f32_e32 v110, v148, v193
	v_fmac_f32_e32 v111, v148, v193
	v_exp_f32_e32 v157, v157
	v_mul_f32_e32 v149, v108, v108
	v_fmac_f32_e32 v149, v109, v109
	v_fmac_f32_e32 v149, v110, v110
	v_fmac_f32_e32 v149, v111, v111
	v_add_f32_e32 v154, 1.0, v154
	v_add_f32_e32 v155, 1.0, v155
	v_add_f32_dpp v149, v149, v149 quad_perm:[1,0,3,2] row_mask:0xf bank_mask:0xf bound_ctrl:1
	v_add_f32_e32 v156, 1.0, v156
	v_add_f32_e32 v157, 1.0, v157
	v_add_f32_dpp v149, v149, v149 quad_perm:[2,3,0,1] row_mask:0xf bank_mask:0xf bound_ctrl:1
	v_rcp_f32_e32 v154, v154
	v_rcp_f32_e32 v155, v155
	v_add_f32_dpp v149, v149, v149 row_half_mirror row_mask:0xf bank_mask:0xf bound_ctrl:1
	v_rcp_f32_e32 v156, v156
	v_rcp_f32_e32 v157, v157
	v_add_f32_dpp v149, v149, v149 row_mirror row_mask:0xf bank_mask:0xf bound_ctrl:1
	v_mul_f32_e32 v154, v154, v150
	v_mul_f32_e32 v155, v155, v151
	v_mul_f32_e32 v156, v156, v152
	v_mul_f32_e32 v157, v157, v153
	v_fma_f32 v149, v149, v194, v189
	s_nop 0
	v_rsq_f32_e32 v149, v149
	s_lshl_b32 s1, s24, 11
	v_add_u32_e32 v148, s1, v176
	v_mul_f32_e32 v108, v108, v149
	v_mul_f32_e32 v109, v109, v149
	v_mul_f32_e32 v110, v110, v149
	v_mul_f32_e32 v111, v111, v149
	v_fma_f32 v108, v160, v108, v164
	v_fma_f32 v109, v161, v109, v165
	v_fma_f32 v110, v162, v110, v166
	v_fma_f32 v111, v163, v111, v167
	v_fmac_f32_e32 v108, v100, v104
	v_fmac_f32_e32 v109, v100, v105
	v_fmac_f32_e32 v110, v100, v106
	v_fmac_f32_e32 v111, v100, v107
	v_mul_f32_e32 v108, v108, v154
	v_mul_f32_e32 v109, v109, v155
	v_mul_f32_e32 v110, v110, v156
	v_mul_f32_e32 v111, v111, v157
	v_bfe_u32 v150, v108, 16, 1
	v_bfe_u32 v151, v109, 16, 1
	v_bfe_u32 v152, v110, 16, 1
	v_bfe_u32 v153, v111, 16, 1
	v_add3_u32 v108, v108, v150, s27
	v_add3_u32 v109, v109, v151, s27
	v_add3_u32 v110, v110, v152, s27
	v_add3_u32 v111, v111, v153, s27
	v_perm_b32 v150, v109, v108, vcc_hi
	v_perm_b32 v151, v111, v110, vcc_hi
	s_nop 0
	global_store_dwordx2 v148, v[150:151], s[94:95]
	s_add_i32 s24, s24, s21
	s_add_i32 vcc_lo, s24, s21
	s_add_i32 vcc_lo, vcc_lo, s21
	s_cmpk_gt_i32 vcc_lo, 0x3fff
	s_cbranch_scc1 .Lb3w_tail1
	s_lshl_b32 s1, vcc_lo, 7
	v_add_u32_e32 v169, s1, v172
	global_load_dwordx4 v[100:103], v169, s[94:95]
	s_lshr_b32 s1, vcc_lo, 11
	s_mul_i32 s1, s1, 0x1800000
	s_and_b32 s2, vcc_lo, 0x7ff
	s_mul_i32 s2, s2, 0x600
	s_add_i32 s1, s1, s2
	v_add_u32_e32 v169, s1, v177
	global_load_dwordx4 v[104:107], v169, s[94:95]
	s_lshl_b32 s1, vcc_lo, 11
	v_add_u32_e32 v169, s1, v174
	global_load_dwordx4 v[108:111], v169, s[94:95]
	s_mul_i32 s1, vcc_lo, 0x1900
	v_add_u32_e32 v169, s1, v175
	global_load_dwordx2 v[112:113], v169, s[94:95]
	s_waitcnt vmcnt(8)
	v_fmac_f32_e32 v122, v116, v118
	v_fmac_f32_e32 v123, v116, v119
	v_fmac_f32_e32 v124, v116, v120
	v_fmac_f32_e32 v125, v116, v121
	v_add_f32_e32 v148, v122, v123
	v_add_f32_e32 v149, v124, v125
	v_lshlrev_b32_e32 v150, 16, v126
	v_add_f32_e32 v148, v148, v149
	v_and_b32_e32 v151, 0xffff0000, v126
	v_lshlrev_b32_e32 v152, 16, v127
	v_add_f32_dpp v148, v148, v148 quad_perm:[1,0,3,2] row_mask:0xf bank_mask:0xf bound_ctrl:1
	v_and_b32_e32 v153, 0xffff0000, v127
	v_mul_f32_e32 v154, 0xbfb8aa3b, v150
	v_add_f32_dpp v148, v148, v148 quad_perm:[2,3,0,1] row_mask:0xf bank_mask:0xf bound_ctrl:1
	v_mul_f32_e32 v155, 0xbfb8aa3b, v151
	v_mul_f32_e32 v156, 0xbfb8aa3b, v152
	v_add_f32_dpp v148, v148, v148 row_half_mirror row_mask:0xf bank_mask:0xf bound_ctrl:1
	v_mul_f32_e32 v157, 0xbfb8aa3b, v153
	v_exp_f32_e32 v154, v154
	v_add_f32_dpp v148, v148, v148 row_mirror row_mask:0xf bank_mask:0xf bound_ctrl:1
	v_exp_f32_e32 v155, v155
	v_exp_f32_e32 v156, v156
	v_fmac_f32_e32 v122, v148, v193
	v_fmac_f32_e32 v123, v148, v193
	v_fmac_f32_e32 v124, v148, v193
	v_fmac_f32_e32 v125, v148, v193
	v_exp_f32_e32 v157, v157
	v_mul_f32_e32 v149, v122, v122
	v_fmac_f32_e32 v149, v123, v123
	v_fmac_f32_e32 v149, v124, v124
	v_fmac_f32_e32 v149, v125, v125
	v_add_f32_e32 v154, 1.0, v154
	v_add_f32_e32 v155, 1.0, v155
	v_add_f32_dpp v149, v149, v149 quad_perm:[1,0,3,2] row_mask:0xf bank_mask:0xf bound_ctrl:1
	v_add_f32_e32 v156, 1.0, v156
	v_add_f32_e32 v157, 1.0, v157
	v_add_f32_dpp v149, v149, v149 quad_perm:[2,3,0,1] row_mask:0xf bank_mask:0xf bound_ctrl:1
	v_rcp_f32_e32 v154, v154
	v_rcp_f32_e32 v155, v155
	v_add_f32_dpp v149, v149, v149 row_half_mirror row_mask:0xf bank_mask:0xf bound_ctrl:1
	v_rcp_f32_e32 v156, v156
	v_rcp_f32_e32 v157, v157
	v_add_f32_dpp v149, v149, v149 row_mirror row_mask:0xf bank_mask:0xf bound_ctrl:1
	v_mul_f32_e32 v154, v154, v150
	v_mul_f32_e32 v155, v155, v151
	v_mul_f32_e32 v156, v156, v152
	v_mul_f32_e32 v157, v157, v153
	v_fma_f32 v149, v149, v194, v189
	s_nop 0
	v_rsq_f32_e32 v149, v149
	s_lshl_b32 s1, s24, 11
	v_add_u32_e32 v148, s1, v176
	v_mul_f32_e32 v122, v122, v149
	v_mul_f32_e32 v123, v123, v149
	v_mul_f32_e32 v124, v124, v149
	v_mul_f32_e32 v125, v125, v149
	v_fma_f32 v122, v160, v122, v164
	v_fma_f32 v123, v161, v123, v165
	v_fma_f32 v124, v162, v124, v166
	v_fma_f32 v125, v163, v125, v167
	v_fmac_f32_e32 v122, v114, v118
	v_fmac_f32_e32 v123, v114, v119
	v_fmac_f32_e32 v124, v114, v120
	v_fmac_f32_e32 v125, v114, v121
	v_mul_f32_e32 v122, v122, v154
	v_mul_f32_e32 v123, v123, v155
	v_mul_f32_e32 v124, v124, v156
	v_mul_f32_e32 v125, v125, v157
	v_bfe_u32 v150, v122, 16, 1
	v_bfe_u32 v151, v123, 16, 1
	v_bfe_u32 v152, v124, 16, 1
	v_bfe_u32 v153, v125, 16, 1
	v_add3_u32 v122, v122, v150, s27
	v_add3_u32 v123, v123, v151, s27
	v_add3_u32 v124, v124, v152, s27
	v_add3_u32 v125, v125, v153, s27
	v_perm_b32 v150, v123, v122, vcc_hi
	v_perm_b32 v151, v125, v124, vcc_hi
	s_nop 0
	global_store_dwordx2 v148, v[150:151], s[94:95]
	s_add_i32 s24, s24, s21
	s_add_i32 vcc_lo, s24, s21
	s_add_i32 vcc_lo, vcc_lo, s21
	s_cmpk_gt_i32 vcc_lo, 0x3fff
	s_cbranch_scc1 .Lb3w_tail2
	s_lshl_b32 s1, vcc_lo, 7
	v_add_u32_e32 v169, s1, v172
	global_load_dwordx4 v[114:117], v169, s[94:95]
	s_lshr_b32 s1, vcc_lo, 11
	s_mul_i32 s1, s1, 0x1800000
	s_and_b32 s2, vcc_lo, 0x7ff
	s_mul_i32 s2, s2, 0x600
	s_add_i32 s1, s1, s2
	v_add_u32_e32 v169, s1, v177
	global_load_dwordx4 v[118:121], v169, s[94:95]
	s_lshl_b32 s1, vcc_lo, 11
	v_add_u32_e32 v169, s1, v174
	global_load_dwordx4 v[122:125], v169, s[94:95]
	s_mul_i32 s1, vcc_lo, 0x1900
	v_add_u32_e32 v169, s1, v175
	global_load_dwordx2 v[126:127], v169, s[94:95]
	s_waitcnt vmcnt(8)
	v_fmac_f32_e32 v142, v136, v138
	v_fmac_f32_e32 v143, v136, v139
	v_fmac_f32_e32 v144, v136, v140
	v_fmac_f32_e32 v145, v136, v141
	v_add_f32_e32 v148, v142, v143
	v_add_f32_e32 v149, v144, v145
	v_lshlrev_b32_e32 v150, 16, v146
	v_add_f32_e32 v148, v148, v149
	v_and_b32_e32 v151, 0xffff0000, v146
	v_lshlrev_b32_e32 v152, 16, v147
	v_add_f32_dpp v148, v148, v148 quad_perm:[1,0,3,2] row_mask:0xf bank_mask:0xf bound_ctrl:1
	v_and_b32_e32 v153, 0xffff0000, v147
	v_mul_f32_e32 v154, 0xbfb8aa3b, v150
	v_add_f32_dpp v148, v148, v148 quad_perm:[2,3,0,1] row_mask:0xf bank_mask:0xf bound_ctrl:1
	v_mul_f32_e32 v155, 0xbfb8aa3b, v151
	v_mul_f32_e32 v156, 0xbfb8aa3b, v152
	v_add_f32_dpp v148, v148, v148 row_half_mirror row_mask:0xf bank_mask:0xf bound_ctrl:1
	v_mul_f32_e32 v157, 0xbfb8aa3b, v153
	v_exp_f32_e32 v154, v154
	v_add_f32_dpp v148, v148, v148 row_mirror row_mask:0xf bank_mask:0xf bound_ctrl:1
	v_exp_f32_e32 v155, v155
	v_exp_f32_e32 v156, v156
	v_fmac_f32_e32 v142, v148, v193
	v_fmac_f32_e32 v143, v148, v193
	v_fmac_f32_e32 v144, v148, v193
	v_fmac_f32_e32 v145, v148, v193
	v_exp_f32_e32 v157, v157
	v_mul_f32_e32 v149, v142, v142
	v_fmac_f32_e32 v149, v143, v143
	v_fmac_f32_e32 v149, v144, v144
	v_fmac_f32_e32 v149, v145, v145
	v_add_f32_e32 v154, 1.0, v154
	v_add_f32_e32 v155, 1.0, v155
	v_add_f32_dpp v149, v149, v149 quad_perm:[1,0,3,2] row_mask:0xf bank_mask:0xf bound_ctrl:1
	v_add_f32_e32 v156, 1.0, v156
	v_add_f32_e32 v157, 1.0, v157
	v_add_f32_dpp v149, v149, v149 quad_perm:[2,3,0,1] row_mask:0xf bank_mask:0xf bound_ctrl:1
	v_rcp_f32_e32 v154, v154
	v_rcp_f32_e32 v155, v155
	v_add_f32_dpp v149, v149, v149 row_half_mirror row_mask:0xf bank_mask:0xf bound_ctrl:1
	v_rcp_f32_e32 v156, v156
	v_rcp_f32_e32 v157, v157
	v_add_f32_dpp v149, v149, v149 row_mirror row_mask:0xf bank_mask:0xf bound_ctrl:1
	v_mul_f32_e32 v154, v154, v150
	v_mul_f32_e32 v155, v155, v151
	v_mul_f32_e32 v156, v156, v152
	v_mul_f32_e32 v157, v157, v153
	v_fma_f32 v149, v149, v194, v189
	s_nop 0
	v_rsq_f32_e32 v149, v149
	s_lshl_b32 s1, s24, 11
	v_add_u32_e32 v148, s1, v176
	v_mul_f32_e32 v142, v142, v149
	v_mul_f32_e32 v143, v143, v149
	v_mul_f32_e32 v144, v144, v149
	v_mul_f32_e32 v145, v145, v149
	v_fma_f32 v142, v160, v142, v164
	v_fma_f32 v143, v161, v143, v165
	v_fma_f32 v144, v162, v144, v166
	v_fma_f32 v145, v163, v145, v167
	v_fmac_f32_e32 v142, v134, v138
	v_fmac_f32_e32 v143, v134, v139
	v_fmac_f32_e32 v144, v134, v140
	v_fmac_f32_e32 v145, v134, v141
	v_mul_f32_e32 v142, v142, v154
	v_mul_f32_e32 v143, v143, v155
	v_mul_f32_e32 v144, v144, v156
	v_mul_f32_e32 v145, v145, v157
	v_bfe_u32 v150, v142, 16, 1
	v_bfe_u32 v151, v143, 16, 1
	v_bfe_u32 v152, v144, 16, 1
	v_bfe_u32 v153, v145, 16, 1
	v_add3_u32 v142, v142, v150, s27
	v_add3_u32 v143, v143, v151, s27
	v_add3_u32 v144, v144, v152, s27
	v_add3_u32 v145, v145, v153, s27
	v_perm_b32 v150, v143, v142, vcc_hi
	v_perm_b32 v151, v145, v144, vcc_hi
	s_nop 0
	global_store_dwordx2 v148, v[150:151], s[94:95]
	s_add_i32 s24, s24, s21
	s_branch .Lb3w_loop
.Lb3w_tail0:
	s_add_i32 vcc_lo, s24, s21
	s_cmpk_gt_i32 vcc_lo, 0x3fff
	s_cbranch_scc1 .Lb3w_last0
	s_waitcnt vmcnt(4)
	v_fmac_f32_e32 v108, v102, v104
	v_fmac_f32_e32 v109, v102, v105
	v_fmac_f32_e32 v110, v102, v106
	v_fmac_f32_e32 v111, v102, v107
	v_add_f32_e32 v148, v108, v109
	v_add_f32_e32 v149, v110, v111
	v_lshlrev_b32_e32 v150, 16, v112
	v_add_f32_e32 v148, v148, v149
	v_and_b32_e32 v151, 0xffff0000, v112
	v_lshlrev_b32_e32 v152, 16, v113
	v_add_f32_dpp v148, v148, v148 quad_perm:[1,0,3,2] row_mask:0xf bank_mask:0xf bound_ctrl:1
	v_and_b32_e32 v153, 0xffff0000, v113
	v_mul_f32_e32 v154, 0xbfb8aa3b, v150
	v_add_f32_dpp v148, v148, v148 quad_perm:[2,3,0,1] row_mask:0xf bank_mask:0xf bound_ctrl:1
	v_mul_f32_e32 v155, 0xbfb8aa3b, v151
	v_mul_f32_e32 v156, 0xbfb8aa3b, v152
	v_add_f32_dpp v148, v148, v148 row_half_mirror row_mask:0xf bank_mask:0xf bound_ctrl:1
	v_mul_f32_e32 v157, 0xbfb8aa3b, v153
	v_exp_f32_e32 v154, v154
	v_add_f32_dpp v148, v148, v148 row_mirror row_mask:0xf bank_mask:0xf bound_ctrl:1
	v_exp_f32_e32 v155, v155
	v_exp_f32_e32 v156, v156
	v_fmac_f32_e32 v108, v148, v193
	v_fmac_f32_e32 v109, v148, v193
	v_fmac_f32_e32 v110, v148, v193
	v_fmac_f32_e32 v111, v148, v193
	v_exp_f32_e32 v157, v157
	v_mul_f32_e32 v149, v108, v108
	v_fmac_f32_e32 v149, v109, v109
	v_fmac_f32_e32 v149, v110, v110
	v_fmac_f32_e32 v149, v111, v111
	v_add_f32_e32 v154, 1.0, v154
	v_add_f32_e32 v155, 1.0, v155
	v_add_f32_dpp v149, v149, v149 quad_perm:[1,0,3,2] row_mask:0xf bank_mask:0xf bound_ctrl:1
	v_add_f32_e32 v156, 1.0, v156
	v_add_f32_e32 v157, 1.0, v157
	v_add_f32_dpp v149, v149, v149 quad_perm:[2,3,0,1] row_mask:0xf bank_mask:0xf bound_ctrl:1
	v_rcp_f32_e32 v154, v154
	v_rcp_f32_e32 v155, v155
	v_add_f32_dpp v149, v149, v149 row_half_mirror row_mask:0xf bank_mask:0xf bound_ctrl:1
	v_rcp_f32_e32 v156, v156
	v_rcp_f32_e32 v157, v157
	v_add_f32_dpp v149, v149, v149 row_mirror row_mask:0xf bank_mask:0xf bound_ctrl:1
	v_mul_f32_e32 v154, v154, v150
	v_mul_f32_e32 v155, v155, v151
	v_mul_f32_e32 v156, v156, v152
	v_mul_f32_e32 v157, v157, v153
	v_fma_f32 v149, v149, v194, v189
	s_nop 0
	v_rsq_f32_e32 v149, v149
	s_lshl_b32 s1, s24, 11
	v_add_u32_e32 v148, s1, v176
	v_mul_f32_e32 v108, v108, v149
	v_mul_f32_e32 v109, v109, v149
	v_mul_f32_e32 v110, v110, v149
	v_mul_f32_e32 v111, v111, v149
	v_fma_f32 v108, v160, v108, v164
	v_fma_f32 v109, v161, v109, v165
	v_fma_f32 v110, v162, v110, v166
	v_fma_f32 v111, v163, v111, v167
	v_fmac_f32_e32 v108, v100, v104
	v_fmac_f32_e32 v109, v100, v105
	v_fmac_f32_e32 v110, v100, v106
	v_fmac_f32_e32 v111, v100, v107
	v_mul_f32_e32 v108, v108, v154
	v_mul_f32_e32 v109, v109, v155
	v_mul_f32_e32 v110, v110, v156
	v_mul_f32_e32 v111, v111, v157
	v_bfe_u32 v150, v108, 16, 1
	v_bfe_u32 v151, v109, 16, 1
	v_bfe_u32 v152, v110, 16, 1
	v_bfe_u32 v153, v111, 16, 1
	v_add3_u32 v108, v108, v150, s27
	v_add3_u32 v109, v109, v151, s27
	v_add3_u32 v110, v110, v152, s27
	v_add3_u32 v111, v111, v153, s27
	v_perm_b32 v150, v109, v108, vcc_hi
	v_perm_b32 v151, v111, v110, vcc_hi
	s_nop 0
	global_store_dwordx2 v148, v[150:151], s[94:95]
	s_waitcnt vmcnt(0)
	v_fmac_f32_e32 v122, v116, v118
	v_fmac_f32_e32 v123, v116, v119
	v_fmac_f32_e32 v124, v116, v120
	v_fmac_f32_e32 v125, v116, v121
	v_add_f32_e32 v148, v122, v123
	v_add_f32_e32 v149, v124, v125
	v_lshlrev_b32_e32 v150, 16, v126
	v_add_f32_e32 v148, v148, v149
	v_and_b32_e32 v151, 0xffff0000, v126
	v_lshlrev_b32_e32 v152, 16, v127
	v_add_f32_dpp v148, v148, v148 quad_perm:[1,0,3,2] row_mask:0xf bank_mask:0xf bound_ctrl:1
	v_and_b32_e32 v153, 0xffff0000, v127
	v_mul_f32_e32 v154, 0xbfb8aa3b, v150
	v_add_f32_dpp v148, v148, v148 quad_perm:[2,3,0,1] row_mask:0xf bank_mask:0xf bound_ctrl:1
	v_mul_f32_e32 v155, 0xbfb8aa3b, v151
	v_mul_f32_e32 v156, 0xbfb8aa3b, v152
	v_add_f32_dpp v148, v148, v148 row_half_mirror row_mask:0xf bank_mask:0xf bound_ctrl:1
	v_mul_f32_e32 v157, 0xbfb8aa3b, v153
	v_exp_f32_e32 v154, v154
	v_add_f32_dpp v148, v148, v148 row_mirror row_mask:0xf bank_mask:0xf bound_ctrl:1
	v_exp_f32_e32 v155, v155
	v_exp_f32_e32 v156, v156
	v_fmac_f32_e32 v122, v148, v193
	v_fmac_f32_e32 v123, v148, v193
	v_fmac_f32_e32 v124, v148, v193
	v_fmac_f32_e32 v125, v148, v193
	v_exp_f32_e32 v157, v157
	v_mul_f32_e32 v149, v122, v122
	v_fmac_f32_e32 v149, v123, v123
	v_fmac_f32_e32 v149, v124, v124
	v_fmac_f32_e32 v149, v125, v125
	v_add_f32_e32 v154, 1.0, v154
	v_add_f32_e32 v155, 1.0, v155
	v_add_f32_dpp v149, v149, v149 quad_perm:[1,0,3,2] row_mask:0xf bank_mask:0xf bound_ctrl:1
	v_add_f32_e32 v156, 1.0, v156
	v_add_f32_e32 v157, 1.0, v157
	v_add_f32_dpp v149, v149, v149 quad_perm:[2,3,0,1] row_mask:0xf bank_mask:0xf bound_ctrl:1
	v_rcp_f32_e32 v154, v154
	v_rcp_f32_e32 v155, v155
	v_add_f32_dpp v149, v149, v149 row_half_mirror row_mask:0xf bank_mask:0xf bound_ctrl:1
	v_rcp_f32_e32 v156, v156
	v_rcp_f32_e32 v157, v157
	v_add_f32_dpp v149, v149, v149 row_mirror row_mask:0xf bank_mask:0xf bound_ctrl:1
	v_mul_f32_e32 v154, v154, v150
	v_mul_f32_e32 v155, v155, v151
	v_mul_f32_e32 v156, v156, v152
	v_mul_f32_e32 v157, v157, v153
	v_fma_f32 v149, v149, v194, v189
	s_nop 0
	v_rsq_f32_e32 v149, v149
	s_lshl_b32 s1, vcc_lo, 11
	v_add_u32_e32 v148, s1, v176
	v_mul_f32_e32 v122, v122, v149
	v_mul_f32_e32 v123, v123, v149
	v_mul_f32_e32 v124, v124, v149
	v_mul_f32_e32 v125, v125, v149
	v_fma_f32 v122, v160, v122, v164
	v_fma_f32 v123, v161, v123, v165
	v_fma_f32 v124, v162, v124, v166
	v_fma_f32 v125, v163, v125, v167
	v_fmac_f32_e32 v122, v114, v118
	v_fmac_f32_e32 v123, v114, v119
	v_fmac_f32_e32 v124, v114, v120
	v_fmac_f32_e32 v125, v114, v121
	v_mul_f32_e32 v122, v122, v154
	v_mul_f32_e32 v123, v123, v155
	v_mul_f32_e32 v124, v124, v156
	v_mul_f32_e32 v125, v125, v157
	v_bfe_u32 v150, v122, 16, 1
	v_bfe_u32 v151, v123, 16, 1
	v_bfe_u32 v152, v124, 16, 1
	v_bfe_u32 v153, v125, 16, 1
	v_add3_u32 v122, v122, v150, s27
	v_add3_u32 v123, v123, v151, s27
	v_add3_u32 v124, v124, v152, s27
	v_add3_u32 v125, v125, v153, s27
	v_perm_b32 v150, v123, v122, vcc_hi
	v_perm_b32 v151, v125, v124, vcc_hi
	s_nop 0
	global_store_dwordx2 v148, v[150:151], s[94:95]
	s_branch .LBB0_197
.Lb3w_tail1:
	s_add_i32 vcc_lo, s24, s21
	s_cmpk_gt_i32 vcc_lo, 0x3fff
	s_cbranch_scc1 .Lb3w_last1
	s_waitcnt vmcnt(4)
	v_fmac_f32_e32 v122, v116, v118
	v_fmac_f32_e32 v123, v116, v119
	v_fmac_f32_e32 v124, v116, v120
	v_fmac_f32_e32 v125, v116, v121
	v_add_f32_e32 v148, v122, v123
	v_add_f32_e32 v149, v124, v125
	v_lshlrev_b32_e32 v150, 16, v126
	v_add_f32_e32 v148, v148, v149
	v_and_b32_e32 v151, 0xffff0000, v126
	v_lshlrev_b32_e32 v152, 16, v127
	v_add_f32_dpp v148, v148, v148 quad_perm:[1,0,3,2] row_mask:0xf bank_mask:0xf bound_ctrl:1
	v_and_b32_e32 v153, 0xffff0000, v127
	v_mul_f32_e32 v154, 0xbfb8aa3b, v150
	v_add_f32_dpp v148, v148, v148 quad_perm:[2,3,0,1] row_mask:0xf bank_mask:0xf bound_ctrl:1
	v_mul_f32_e32 v155, 0xbfb8aa3b, v151
	v_mul_f32_e32 v156, 0xbfb8aa3b, v152
	v_add_f32_dpp v148, v148, v148 row_half_mirror row_mask:0xf bank_mask:0xf bound_ctrl:1
	v_mul_f32_e32 v157, 0xbfb8aa3b, v153
	v_exp_f32_e32 v154, v154
	v_add_f32_dpp v148, v148, v148 row_mirror row_mask:0xf bank_mask:0xf bound_ctrl:1
	v_exp_f32_e32 v155, v155
	v_exp_f32_e32 v156, v156
	v_fmac_f32_e32 v122, v148, v193
	v_fmac_f32_e32 v123, v148, v193
	v_fmac_f32_e32 v124, v148, v193
	v_fmac_f32_e32 v125, v148, v193
	v_exp_f32_e32 v157, v157
	v_mul_f32_e32 v149, v122, v122
	v_fmac_f32_e32 v149, v123, v123
	v_fmac_f32_e32 v149, v124, v124
	v_fmac_f32_e32 v149, v125, v125
	v_add_f32_e32 v154, 1.0, v154
	v_add_f32_e32 v155, 1.0, v155
	v_add_f32_dpp v149, v149, v149 quad_perm:[1,0,3,2] row_mask:0xf bank_mask:0xf bound_ctrl:1
	v_add_f32_e32 v156, 1.0, v156
	v_add_f32_e32 v157, 1.0, v157
	v_add_f32_dpp v149, v149, v149 quad_perm:[2,3,0,1] row_mask:0xf bank_mask:0xf bound_ctrl:1
	v_rcp_f32_e32 v154, v154
	v_rcp_f32_e32 v155, v155
	v_add_f32_dpp v149, v149, v149 row_half_mirror row_mask:0xf bank_mask:0xf bound_ctrl:1
	v_rcp_f32_e32 v156, v156
	v_rcp_f32_e32 v157, v157
	v_add_f32_dpp v149, v149, v149 row_mirror row_mask:0xf bank_mask:0xf bound_ctrl:1
	v_mul_f32_e32 v154, v154, v150
	v_mul_f32_e32 v155, v155, v151
	v_mul_f32_e32 v156, v156, v152
	v_mul_f32_e32 v157, v157, v153
	v_fma_f32 v149, v149, v194, v189
	s_nop 0
	v_rsq_f32_e32 v149, v149
	s_lshl_b32 s1, s24, 11
	v_add_u32_e32 v148, s1, v176
	v_mul_f32_e32 v122, v122, v149
	v_mul_f32_e32 v123, v123, v149
	v_mul_f32_e32 v124, v124, v149
	v_mul_f32_e32 v125, v125, v149
	v_fma_f32 v122, v160, v122, v164
	v_fma_f32 v123, v161, v123, v165
	v_fma_f32 v124, v162, v124, v166
	v_fma_f32 v125, v163, v125, v167
	v_fmac_f32_e32 v122, v114, v118
	v_fmac_f32_e32 v123, v114, v119
	v_fmac_f32_e32 v124, v114, v120
	v_fmac_f32_e32 v125, v114, v121
	v_mul_f32_e32 v122, v122, v154
	v_mul_f32_e32 v123, v123, v155
	v_mul_f32_e32 v124, v124, v156
	v_mul_f32_e32 v125, v125, v157
	v_bfe_u32 v150, v122, 16, 1
	v_bfe_u32 v151, v123, 16, 1
	v_bfe_u32 v152, v124, 16, 1
	v_bfe_u32 v153, v125, 16, 1
	v_add3_u32 v122, v122, v150, s27
	v_add3_u32 v123, v123, v151, s27
	v_add3_u32 v124, v124, v152, s27
	v_add3_u32 v125, v125, v153, s27
	v_perm_b32 v150, v123, v122, vcc_hi
	v_perm_b32 v151, v125, v124, vcc_hi
	s_nop 0
	global_store_dwordx2 v148, v[150:151], s[94:95]
	s_waitcnt vmcnt(0)
	v_fmac_f32_e32 v142, v136, v138
	v_fmac_f32_e32 v143, v136, v139
	v_fmac_f32_e32 v144, v136, v140
	v_fmac_f32_e32 v145, v136, v141
	v_add_f32_e32 v148, v142, v143
	v_add_f32_e32 v149, v144, v145
	v_lshlrev_b32_e32 v150, 16, v146
	v_add_f32_e32 v148, v148, v149
	v_and_b32_e32 v151, 0xffff0000, v146
	v_lshlrev_b32_e32 v152, 16, v147
	v_add_f32_dpp v148, v148, v148 quad_perm:[1,0,3,2] row_mask:0xf bank_mask:0xf bound_ctrl:1
	v_and_b32_e32 v153, 0xffff0000, v147
	v_mul_f32_e32 v154, 0xbfb8aa3b, v150
	v_add_f32_dpp v148, v148, v148 quad_perm:[2,3,0,1] row_mask:0xf bank_mask:0xf bound_ctrl:1
	v_mul_f32_e32 v155, 0xbfb8aa3b, v151
	v_mul_f32_e32 v156, 0xbfb8aa3b, v152
	v_add_f32_dpp v148, v148, v148 row_half_mirror row_mask:0xf bank_mask:0xf bound_ctrl:1
	v_mul_f32_e32 v157, 0xbfb8aa3b, v153
	v_exp_f32_e32 v154, v154
	v_add_f32_dpp v148, v148, v148 row_mirror row_mask:0xf bank_mask:0xf bound_ctrl:1
	v_exp_f32_e32 v155, v155
	v_exp_f32_e32 v156, v156
	v_fmac_f32_e32 v142, v148, v193
	v_fmac_f32_e32 v143, v148, v193
	v_fmac_f32_e32 v144, v148, v193
	v_fmac_f32_e32 v145, v148, v193
	v_exp_f32_e32 v157, v157
	v_mul_f32_e32 v149, v142, v142
	v_fmac_f32_e32 v149, v143, v143
	v_fmac_f32_e32 v149, v144, v144
	v_fmac_f32_e32 v149, v145, v145
	v_add_f32_e32 v154, 1.0, v154
	v_add_f32_e32 v155, 1.0, v155
	v_add_f32_dpp v149, v149, v149 quad_perm:[1,0,3,2] row_mask:0xf bank_mask:0xf bound_ctrl:1
	v_add_f32_e32 v156, 1.0, v156
	v_add_f32_e32 v157, 1.0, v157
	v_add_f32_dpp v149, v149, v149 quad_perm:[2,3,0,1] row_mask:0xf bank_mask:0xf bound_ctrl:1
	v_rcp_f32_e32 v154, v154
	v_rcp_f32_e32 v155, v155
	v_add_f32_dpp v149, v149, v149 row_half_mirror row_mask:0xf bank_mask:0xf bound_ctrl:1
	v_rcp_f32_e32 v156, v156
	v_rcp_f32_e32 v157, v157
	v_add_f32_dpp v149, v149, v149 row_mirror row_mask:0xf bank_mask:0xf bound_ctrl:1
	v_mul_f32_e32 v154, v154, v150
	v_mul_f32_e32 v155, v155, v151
	v_mul_f32_e32 v156, v156, v152
	v_mul_f32_e32 v157, v157, v153
	v_fma_f32 v149, v149, v194, v189
	s_nop 0
	v_rsq_f32_e32 v149, v149
	s_lshl_b32 s1, vcc_lo, 11
	v_add_u32_e32 v148, s1, v176
	v_mul_f32_e32 v142, v142, v149
	v_mul_f32_e32 v143, v143, v149
	v_mul_f32_e32 v144, v144, v149
	v_mul_f32_e32 v145, v145, v149
	v_fma_f32 v142, v160, v142, v164
	v_fma_f32 v143, v161, v143, v165
	v_fma_f32 v144, v162, v144, v166
	v_fma_f32 v145, v163, v145, v167
	v_fmac_f32_e32 v142, v134, v138
	v_fmac_f32_e32 v143, v134, v139
	v_fmac_f32_e32 v144, v134, v140
	v_fmac_f32_e32 v145, v134, v141
	v_mul_f32_e32 v142, v142, v154
	v_mul_f32_e32 v143, v143, v155
	v_mul_f32_e32 v144, v144, v156
	v_mul_f32_e32 v145, v145, v157
	v_bfe_u32 v150, v142, 16, 1
	v_bfe_u32 v151, v143, 16, 1
	v_bfe_u32 v152, v144, 16, 1
	v_bfe_u32 v153, v145, 16, 1
	v_add3_u32 v142, v142, v150, s27
	v_add3_u32 v143, v143, v151, s27
	v_add3_u32 v144, v144, v152, s27
	v_add3_u32 v145, v145, v153, s27
	v_perm_b32 v150, v143, v142, vcc_hi
	v_perm_b32 v151, v145, v144, vcc_hi
	s_nop 0
	global_store_dwordx2 v148, v[150:151], s[94:95]
	s_branch .LBB0_197
.Lb3w_tail2:
	s_add_i32 vcc_lo, s24, s21
	s_cmpk_gt_i32 vcc_lo, 0x3fff
	s_cbranch_scc1 .Lb3w_last2
	s_waitcnt vmcnt(4)
	v_fmac_f32_e32 v142, v136, v138
	v_fmac_f32_e32 v143, v136, v139
	v_fmac_f32_e32 v144, v136, v140
	v_fmac_f32_e32 v145, v136, v141
	v_add_f32_e32 v148, v142, v143
	v_add_f32_e32 v149, v144, v145
	v_lshlrev_b32_e32 v150, 16, v146
	v_add_f32_e32 v148, v148, v149
	v_and_b32_e32 v151, 0xffff0000, v146
	v_lshlrev_b32_e32 v152, 16, v147
	v_add_f32_dpp v148, v148, v148 quad_perm:[1,0,3,2] row_mask:0xf bank_mask:0xf bound_ctrl:1
	v_and_b32_e32 v153, 0xffff0000, v147
	v_mul_f32_e32 v154, 0xbfb8aa3b, v150
	v_add_f32_dpp v148, v148, v148 quad_perm:[2,3,0,1] row_mask:0xf bank_mask:0xf bound_ctrl:1
	v_mul_f32_e32 v155, 0xbfb8aa3b, v151
	v_mul_f32_e32 v156, 0xbfb8aa3b, v152
	v_add_f32_dpp v148, v148, v148 row_half_mirror row_mask:0xf bank_mask:0xf bound_ctrl:1
	v_mul_f32_e32 v157, 0xbfb8aa3b, v153
	v_exp_f32_e32 v154, v154
	v_add_f32_dpp v148, v148, v148 row_mirror row_mask:0xf bank_mask:0xf bound_ctrl:1
	v_exp_f32_e32 v155, v155
	v_exp_f32_e32 v156, v156
	v_fmac_f32_e32 v142, v148, v193
	v_fmac_f32_e32 v143, v148, v193
	v_fmac_f32_e32 v144, v148, v193
	v_fmac_f32_e32 v145, v148, v193
	v_exp_f32_e32 v157, v157
	v_mul_f32_e32 v149, v142, v142
	v_fmac_f32_e32 v149, v143, v143
	v_fmac_f32_e32 v149, v144, v144
	v_fmac_f32_e32 v149, v145, v145
	v_add_f32_e32 v154, 1.0, v154
	v_add_f32_e32 v155, 1.0, v155
	v_add_f32_dpp v149, v149, v149 quad_perm:[1,0,3,2] row_mask:0xf bank_mask:0xf bound_ctrl:1
	v_add_f32_e32 v156, 1.0, v156
	v_add_f32_e32 v157, 1.0, v157
	v_add_f32_dpp v149, v149, v149 quad_perm:[2,3,0,1] row_mask:0xf bank_mask:0xf bound_ctrl:1
	v_rcp_f32_e32 v154, v154
	v_rcp_f32_e32 v155, v155
	v_add_f32_dpp v149, v149, v149 row_half_mirror row_mask:0xf bank_mask:0xf bound_ctrl:1
	v_rcp_f32_e32 v156, v156
	v_rcp_f32_e32 v157, v157
	v_add_f32_dpp v149, v149, v149 row_mirror row_mask:0xf bank_mask:0xf bound_ctrl:1
	v_mul_f32_e32 v154, v154, v150
	v_mul_f32_e32 v155, v155, v151
	v_mul_f32_e32 v156, v156, v152
	v_mul_f32_e32 v157, v157, v153
	v_fma_f32 v149, v149, v194, v189
	s_nop 0
	v_rsq_f32_e32 v149, v149
	s_lshl_b32 s1, s24, 11
	v_add_u32_e32 v148, s1, v176
	v_mul_f32_e32 v142, v142, v149
	v_mul_f32_e32 v143, v143, v149
	v_mul_f32_e32 v144, v144, v149
	v_mul_f32_e32 v145, v145, v149
	v_fma_f32 v142, v160, v142, v164
	v_fma_f32 v143, v161, v143, v165
	v_fma_f32 v144, v162, v144, v166
	v_fma_f32 v145, v163, v145, v167
	v_fmac_f32_e32 v142, v134, v138
	v_fmac_f32_e32 v143, v134, v139
	v_fmac_f32_e32 v144, v134, v140
	v_fmac_f32_e32 v145, v134, v141
	v_mul_f32_e32 v142, v142, v154
	v_mul_f32_e32 v143, v143, v155
	v_mul_f32_e32 v144, v144, v156
	v_mul_f32_e32 v145, v145, v157
	v_bfe_u32 v150, v142, 16, 1
	v_bfe_u32 v151, v143, 16, 1
	v_bfe_u32 v152, v144, 16, 1
	v_bfe_u32 v153, v145, 16, 1
	v_add3_u32 v142, v142, v150, s27
	v_add3_u32 v143, v143, v151, s27
	v_add3_u32 v144, v144, v152, s27
	v_add3_u32 v145, v145, v153, s27
	v_perm_b32 v150, v143, v142, vcc_hi
	v_perm_b32 v151, v145, v144, vcc_hi
	s_nop 0
	global_store_dwordx2 v148, v[150:151], s[94:95]
	s_waitcnt vmcnt(0)
	v_fmac_f32_e32 v108, v102, v104
	v_fmac_f32_e32 v109, v102, v105
	v_fmac_f32_e32 v110, v102, v106
	v_fmac_f32_e32 v111, v102, v107
	v_add_f32_e32 v148, v108, v109
	v_add_f32_e32 v149, v110, v111
	v_lshlrev_b32_e32 v150, 16, v112
	v_add_f32_e32 v148, v148, v149
	v_and_b32_e32 v151, 0xffff0000, v112
	v_lshlrev_b32_e32 v152, 16, v113
	v_add_f32_dpp v148, v148, v148 quad_perm:[1,0,3,2] row_mask:0xf bank_mask:0xf bound_ctrl:1
	v_and_b32_e32 v153, 0xffff0000, v113
	v_mul_f32_e32 v154, 0xbfb8aa3b, v150
	v_add_f32_dpp v148, v148, v148 quad_perm:[2,3,0,1] row_mask:0xf bank_mask:0xf bound_ctrl:1
	v_mul_f32_e32 v155, 0xbfb8aa3b, v151
	v_mul_f32_e32 v156, 0xbfb8aa3b, v152
	v_add_f32_dpp v148, v148, v148 row_half_mirror row_mask:0xf bank_mask:0xf bound_ctrl:1
	v_mul_f32_e32 v157, 0xbfb8aa3b, v153
	v_exp_f32_e32 v154, v154
	v_add_f32_dpp v148, v148, v148 row_mirror row_mask:0xf bank_mask:0xf bound_ctrl:1
	v_exp_f32_e32 v155, v155
	v_exp_f32_e32 v156, v156
	v_fmac_f32_e32 v108, v148, v193
	v_fmac_f32_e32 v109, v148, v193
	v_fmac_f32_e32 v110, v148, v193
	v_fmac_f32_e32 v111, v148, v193
	v_exp_f32_e32 v157, v157
	v_mul_f32_e32 v149, v108, v108
	v_fmac_f32_e32 v149, v109, v109
	v_fmac_f32_e32 v149, v110, v110
	v_fmac_f32_e32 v149, v111, v111
	v_add_f32_e32 v154, 1.0, v154
	v_add_f32_e32 v155, 1.0, v155
	v_add_f32_dpp v149, v149, v149 quad_perm:[1,0,3,2] row_mask:0xf bank_mask:0xf bound_ctrl:1
	v_add_f32_e32 v156, 1.0, v156
	v_add_f32_e32 v157, 1.0, v157
	v_add_f32_dpp v149, v149, v149 quad_perm:[2,3,0,1] row_mask:0xf bank_mask:0xf bound_ctrl:1
	v_rcp_f32_e32 v154, v154
	v_rcp_f32_e32 v155, v155
	v_add_f32_dpp v149, v149, v149 row_half_mirror row_mask:0xf bank_mask:0xf bound_ctrl:1
	v_rcp_f32_e32 v156, v156
	v_rcp_f32_e32 v157, v157
	v_add_f32_dpp v149, v149, v149 row_mirror row_mask:0xf bank_mask:0xf bound_ctrl:1
	v_mul_f32_e32 v154, v154, v150
	v_mul_f32_e32 v155, v155, v151
	v_mul_f32_e32 v156, v156, v152
	v_mul_f32_e32 v157, v157, v153
	v_fma_f32 v149, v149, v194, v189
	s_nop 0
	v_rsq_f32_e32 v149, v149
	s_lshl_b32 s1, vcc_lo, 11
	v_add_u32_e32 v148, s1, v176
	v_mul_f32_e32 v108, v108, v149
	v_mul_f32_e32 v109, v109, v149
	v_mul_f32_e32 v110, v110, v149
	v_mul_f32_e32 v111, v111, v149
	v_fma_f32 v108, v160, v108, v164
	v_fma_f32 v109, v161, v109, v165
	v_fma_f32 v110, v162, v110, v166
	v_fma_f32 v111, v163, v111, v167
	v_fmac_f32_e32 v108, v100, v104
	v_fmac_f32_e32 v109, v100, v105
	v_fmac_f32_e32 v110, v100, v106
	v_fmac_f32_e32 v111, v100, v107
	v_mul_f32_e32 v108, v108, v154
	v_mul_f32_e32 v109, v109, v155
	v_mul_f32_e32 v110, v110, v156
	v_mul_f32_e32 v111, v111, v157
	v_bfe_u32 v150, v108, 16, 1
	v_bfe_u32 v151, v109, 16, 1
	v_bfe_u32 v152, v110, 16, 1
	v_bfe_u32 v153, v111, 16, 1
	v_add3_u32 v108, v108, v150, s27
	v_add3_u32 v109, v109, v151, s27
	v_add3_u32 v110, v110, v152, s27
	v_add3_u32 v111, v111, v153, s27
	v_perm_b32 v150, v109, v108, vcc_hi
	v_perm_b32 v151, v111, v110, vcc_hi
	s_nop 0
	global_store_dwordx2 v148, v[150:151], s[94:95]
	s_branch .LBB0_197
.Lb3w_last0:
	s_waitcnt vmcnt(0)
	v_fmac_f32_e32 v108, v102, v104
	v_fmac_f32_e32 v109, v102, v105
	v_fmac_f32_e32 v110, v102, v106
	v_fmac_f32_e32 v111, v102, v107
	v_add_f32_e32 v148, v108, v109
	v_add_f32_e32 v149, v110, v111
	v_lshlrev_b32_e32 v150, 16, v112
	v_add_f32_e32 v148, v148, v149
	v_and_b32_e32 v151, 0xffff0000, v112
	v_lshlrev_b32_e32 v152, 16, v113
	v_add_f32_dpp v148, v148, v148 quad_perm:[1,0,3,2] row_mask:0xf bank_mask:0xf bound_ctrl:1
	v_and_b32_e32 v153, 0xffff0000, v113
	v_mul_f32_e32 v154, 0xbfb8aa3b, v150
	v_add_f32_dpp v148, v148, v148 quad_perm:[2,3,0,1] row_mask:0xf bank_mask:0xf bound_ctrl:1
	v_mul_f32_e32 v155, 0xbfb8aa3b, v151
	v_mul_f32_e32 v156, 0xbfb8aa3b, v152
	v_add_f32_dpp v148, v148, v148 row_half_mirror row_mask:0xf bank_mask:0xf bound_ctrl:1
	v_mul_f32_e32 v157, 0xbfb8aa3b, v153
	v_exp_f32_e32 v154, v154
	v_add_f32_dpp v148, v148, v148 row_mirror row_mask:0xf bank_mask:0xf bound_ctrl:1
	v_exp_f32_e32 v155, v155
	v_exp_f32_e32 v156, v156
	v_fmac_f32_e32 v108, v148, v193
	v_fmac_f32_e32 v109, v148, v193
	v_fmac_f32_e32 v110, v148, v193
	v_fmac_f32_e32 v111, v148, v193
	v_exp_f32_e32 v157, v157
	v_mul_f32_e32 v149, v108, v108
	v_fmac_f32_e32 v149, v109, v109
	v_fmac_f32_e32 v149, v110, v110
	v_fmac_f32_e32 v149, v111, v111
	v_add_f32_e32 v154, 1.0, v154
	v_add_f32_e32 v155, 1.0, v155
	v_add_f32_dpp v149, v149, v149 quad_perm:[1,0,3,2] row_mask:0xf bank_mask:0xf bound_ctrl:1
	v_add_f32_e32 v156, 1.0, v156
	v_add_f32_e32 v157, 1.0, v157
	v_add_f32_dpp v149, v149, v149 quad_perm:[2,3,0,1] row_mask:0xf bank_mask:0xf bound_ctrl:1
	v_rcp_f32_e32 v154, v154
	v_rcp_f32_e32 v155, v155
	v_add_f32_dpp v149, v149, v149 row_half_mirror row_mask:0xf bank_mask:0xf bound_ctrl:1
	v_rcp_f32_e32 v156, v156
	v_rcp_f32_e32 v157, v157
	v_add_f32_dpp v149, v149, v149 row_mirror row_mask:0xf bank_mask:0xf bound_ctrl:1
	v_mul_f32_e32 v154, v154, v150
	v_mul_f32_e32 v155, v155, v151
	v_mul_f32_e32 v156, v156, v152
	v_mul_f32_e32 v157, v157, v153
	v_fma_f32 v149, v149, v194, v189
	s_nop 0
	v_rsq_f32_e32 v149, v149
	s_lshl_b32 s1, s24, 11
	v_add_u32_e32 v148, s1, v176
	v_mul_f32_e32 v108, v108, v149
	v_mul_f32_e32 v109, v109, v149
	v_mul_f32_e32 v110, v110, v149
	v_mul_f32_e32 v111, v111, v149
	v_fma_f32 v108, v160, v108, v164
	v_fma_f32 v109, v161, v109, v165
	v_fma_f32 v110, v162, v110, v166
	v_fma_f32 v111, v163, v111, v167
	v_fmac_f32_e32 v108, v100, v104
	v_fmac_f32_e32 v109, v100, v105
	v_fmac_f32_e32 v110, v100, v106
	v_fmac_f32_e32 v111, v100, v107
	v_mul_f32_e32 v108, v108, v154
	v_mul_f32_e32 v109, v109, v155
	v_mul_f32_e32 v110, v110, v156
	v_mul_f32_e32 v111, v111, v157
	v_bfe_u32 v150, v108, 16, 1
	v_bfe_u32 v151, v109, 16, 1
	v_bfe_u32 v152, v110, 16, 1
	v_bfe_u32 v153, v111, 16, 1
	v_add3_u32 v108, v108, v150, s27
	v_add3_u32 v109, v109, v151, s27
	v_add3_u32 v110, v110, v152, s27
	v_add3_u32 v111, v111, v153, s27
	v_perm_b32 v150, v109, v108, vcc_hi
	v_perm_b32 v151, v111, v110, vcc_hi
	s_nop 0
	global_store_dwordx2 v148, v[150:151], s[94:95]
	s_branch .LBB0_197
.Lb3w_last1:
	s_waitcnt vmcnt(0)
	v_fmac_f32_e32 v122, v116, v118
	v_fmac_f32_e32 v123, v116, v119
	v_fmac_f32_e32 v124, v116, v120
	v_fmac_f32_e32 v125, v116, v121
	v_add_f32_e32 v148, v122, v123
	v_add_f32_e32 v149, v124, v125
	v_lshlrev_b32_e32 v150, 16, v126
	v_add_f32_e32 v148, v148, v149
	v_and_b32_e32 v151, 0xffff0000, v126
	v_lshlrev_b32_e32 v152, 16, v127
	v_add_f32_dpp v148, v148, v148 quad_perm:[1,0,3,2] row_mask:0xf bank_mask:0xf bound_ctrl:1
	v_and_b32_e32 v153, 0xffff0000, v127
	v_mul_f32_e32 v154, 0xbfb8aa3b, v150
	v_add_f32_dpp v148, v148, v148 quad_perm:[2,3,0,1] row_mask:0xf bank_mask:0xf bound_ctrl:1
	v_mul_f32_e32 v155, 0xbfb8aa3b, v151
	v_mul_f32_e32 v156, 0xbfb8aa3b, v152
	v_add_f32_dpp v148, v148, v148 row_half_mirror row_mask:0xf bank_mask:0xf bound_ctrl:1
	v_mul_f32_e32 v157, 0xbfb8aa3b, v153
	v_exp_f32_e32 v154, v154
	v_add_f32_dpp v148, v148, v148 row_mirror row_mask:0xf bank_mask:0xf bound_ctrl:1
	v_exp_f32_e32 v155, v155
	v_exp_f32_e32 v156, v156
	v_fmac_f32_e32 v122, v148, v193
	v_fmac_f32_e32 v123, v148, v193
	v_fmac_f32_e32 v124, v148, v193
	v_fmac_f32_e32 v125, v148, v193
	v_exp_f32_e32 v157, v157
	v_mul_f32_e32 v149, v122, v122
	v_fmac_f32_e32 v149, v123, v123
	v_fmac_f32_e32 v149, v124, v124
	v_fmac_f32_e32 v149, v125, v125
	v_add_f32_e32 v154, 1.0, v154
	v_add_f32_e32 v155, 1.0, v155
	v_add_f32_dpp v149, v149, v149 quad_perm:[1,0,3,2] row_mask:0xf bank_mask:0xf bound_ctrl:1
	v_add_f32_e32 v156, 1.0, v156
	v_add_f32_e32 v157, 1.0, v157
	v_add_f32_dpp v149, v149, v149 quad_perm:[2,3,0,1] row_mask:0xf bank_mask:0xf bound_ctrl:1
	v_rcp_f32_e32 v154, v154
	v_rcp_f32_e32 v155, v155
	v_add_f32_dpp v149, v149, v149 row_half_mirror row_mask:0xf bank_mask:0xf bound_ctrl:1
	v_rcp_f32_e32 v156, v156
	v_rcp_f32_e32 v157, v157
	v_add_f32_dpp v149, v149, v149 row_mirror row_mask:0xf bank_mask:0xf bound_ctrl:1
	v_mul_f32_e32 v154, v154, v150
	v_mul_f32_e32 v155, v155, v151
	v_mul_f32_e32 v156, v156, v152
	v_mul_f32_e32 v157, v157, v153
	v_fma_f32 v149, v149, v194, v189
	s_nop 0
	v_rsq_f32_e32 v149, v149
	s_lshl_b32 s1, s24, 11
	v_add_u32_e32 v148, s1, v176
	v_mul_f32_e32 v122, v122, v149
	v_mul_f32_e32 v123, v123, v149
	v_mul_f32_e32 v124, v124, v149
	v_mul_f32_e32 v125, v125, v149
	v_fma_f32 v122, v160, v122, v164
	v_fma_f32 v123, v161, v123, v165
	v_fma_f32 v124, v162, v124, v166
	v_fma_f32 v125, v163, v125, v167
	v_fmac_f32_e32 v122, v114, v118
	v_fmac_f32_e32 v123, v114, v119
	v_fmac_f32_e32 v124, v114, v120
	v_fmac_f32_e32 v125, v114, v121
	v_mul_f32_e32 v122, v122, v154
	v_mul_f32_e32 v123, v123, v155
	v_mul_f32_e32 v124, v124, v156
	v_mul_f32_e32 v125, v125, v157
	v_bfe_u32 v150, v122, 16, 1
	v_bfe_u32 v151, v123, 16, 1
	v_bfe_u32 v152, v124, 16, 1
	v_bfe_u32 v153, v125, 16, 1
	v_add3_u32 v122, v122, v150, s27
	v_add3_u32 v123, v123, v151, s27
	v_add3_u32 v124, v124, v152, s27
	v_add3_u32 v125, v125, v153, s27
	v_perm_b32 v150, v123, v122, vcc_hi
	v_perm_b32 v151, v125, v124, vcc_hi
	s_nop 0
	global_store_dwordx2 v148, v[150:151], s[94:95]
	s_branch .LBB0_197
.Lb3w_last2:
	s_waitcnt vmcnt(0)
	v_fmac_f32_e32 v142, v136, v138
	v_fmac_f32_e32 v143, v136, v139
	v_fmac_f32_e32 v144, v136, v140
	v_fmac_f32_e32 v145, v136, v141
	v_add_f32_e32 v148, v142, v143
	v_add_f32_e32 v149, v144, v145
	v_lshlrev_b32_e32 v150, 16, v146
	v_add_f32_e32 v148, v148, v149
	v_and_b32_e32 v151, 0xffff0000, v146
	v_lshlrev_b32_e32 v152, 16, v147
	v_add_f32_dpp v148, v148, v148 quad_perm:[1,0,3,2] row_mask:0xf bank_mask:0xf bound_ctrl:1
	v_and_b32_e32 v153, 0xffff0000, v147
	v_mul_f32_e32 v154, 0xbfb8aa3b, v150
	v_add_f32_dpp v148, v148, v148 quad_perm:[2,3,0,1] row_mask:0xf bank_mask:0xf bound_ctrl:1
	v_mul_f32_e32 v155, 0xbfb8aa3b, v151
	v_mul_f32_e32 v156, 0xbfb8aa3b, v152
	v_add_f32_dpp v148, v148, v148 row_half_mirror row_mask:0xf bank_mask:0xf bound_ctrl:1
	v_mul_f32_e32 v157, 0xbfb8aa3b, v153
	v_exp_f32_e32 v154, v154
	v_add_f32_dpp v148, v148, v148 row_mirror row_mask:0xf bank_mask:0xf bound_ctrl:1
	v_exp_f32_e32 v155, v155
	v_exp_f32_e32 v156, v156
	v_fmac_f32_e32 v142, v148, v193
	v_fmac_f32_e32 v143, v148, v193
	v_fmac_f32_e32 v144, v148, v193
	v_fmac_f32_e32 v145, v148, v193
	v_exp_f32_e32 v157, v157
	v_mul_f32_e32 v149, v142, v142
	v_fmac_f32_e32 v149, v143, v143
	v_fmac_f32_e32 v149, v144, v144
	v_fmac_f32_e32 v149, v145, v145
	v_add_f32_e32 v154, 1.0, v154
	v_add_f32_e32 v155, 1.0, v155
	v_add_f32_dpp v149, v149, v149 quad_perm:[1,0,3,2] row_mask:0xf bank_mask:0xf bound_ctrl:1
	v_add_f32_e32 v156, 1.0, v156
	v_add_f32_e32 v157, 1.0, v157
	v_add_f32_dpp v149, v149, v149 quad_perm:[2,3,0,1] row_mask:0xf bank_mask:0xf bound_ctrl:1
	v_rcp_f32_e32 v154, v154
	v_rcp_f32_e32 v155, v155
	v_add_f32_dpp v149, v149, v149 row_half_mirror row_mask:0xf bank_mask:0xf bound_ctrl:1
	v_rcp_f32_e32 v156, v156
	v_rcp_f32_e32 v157, v157
	v_add_f32_dpp v149, v149, v149 row_mirror row_mask:0xf bank_mask:0xf bound_ctrl:1
	v_mul_f32_e32 v154, v154, v150
	v_mul_f32_e32 v155, v155, v151
	v_mul_f32_e32 v156, v156, v152
	v_mul_f32_e32 v157, v157, v153
	v_fma_f32 v149, v149, v194, v189
	s_nop 0
	v_rsq_f32_e32 v149, v149
	s_lshl_b32 s1, s24, 11
	v_add_u32_e32 v148, s1, v176
	v_mul_f32_e32 v142, v142, v149
	v_mul_f32_e32 v143, v143, v149
	v_mul_f32_e32 v144, v144, v149
	v_mul_f32_e32 v145, v145, v149
	v_fma_f32 v142, v160, v142, v164
	v_fma_f32 v143, v161, v143, v165
	v_fma_f32 v144, v162, v144, v166
	v_fma_f32 v145, v163, v145, v167
	v_fmac_f32_e32 v142, v134, v138
	v_fmac_f32_e32 v143, v134, v139
	v_fmac_f32_e32 v144, v134, v140
	v_fmac_f32_e32 v145, v134, v141
	v_mul_f32_e32 v142, v142, v154
	v_mul_f32_e32 v143, v143, v155
	v_mul_f32_e32 v144, v144, v156
	v_mul_f32_e32 v145, v145, v157
	v_bfe_u32 v150, v142, 16, 1
	v_bfe_u32 v151, v143, 16, 1
	v_bfe_u32 v152, v144, 16, 1
	v_bfe_u32 v153, v145, 16, 1
	v_add3_u32 v142, v142, v150, s27
	v_add3_u32 v143, v143, v151, s27
	v_add3_u32 v144, v144, v152, s27
	v_add3_u32 v145, v145, v153, s27
	v_perm_b32 v150, v143, v142, vcc_hi
	v_perm_b32 v151, v145, v144, vcc_hi
	s_nop 0
	global_store_dwordx2 v148, v[150:151], s[94:95]
	s_branch .LBB0_197

.LBB0_213:
	v_lshrrev_b32_e32 v170, 6, v133
	v_bfe_u32 v171, v133, 4, 2
	v_and_b32_e32 v173, 15, v133
	v_lshlrev_b32_e32 v173, 2, v173
	v_lshl_add_u32 v173, v170, 6, v173
	v_lshlrev_b32_e32 v172, 4, v170
	v_lshl_add_u32 v172, v171, 7, v172
	v_add_u32_e32 v172, 0x19110000, v172
	v_lshlrev_b32_e32 v174, 2, v173
	v_lshl_add_u32 v174, v171, 11, v174
	v_add_u32_e32 v174, 0x19314000, v174
	v_mul_u32_u24_e32 v175, 0x1900, v171
	v_lshl_add_u32 v175, v173, 1, v175
	v_add_u32_e32 v175, 0x6a01100, v175
	v_lshlrev_b32_e32 v176, 1, v173
	v_lshl_add_u32 v176, v171, 11, v176
	v_add_u32_e32 v176, 0x4580200, v176
	v_mul_u32_u24_e32 v177, 0x600, v170
	v_mul_u32_u24_e32 v178, 0x3000, v171
	v_add_u32_e32 v177, v177, v178
	v_and_b32_e32 v178, 15, v133
	v_lshl_add_u32 v177, v178, 4, v177
	v_add_u32_e32 v177, 0xcf90500, v177
	v_readlane_b32 s0, v215, 36
	v_readlane_b32 s1, v215, 37
	s_lshl_b32 s2, s76, 9
	v_add_u32_e32 v178, s2, v173
	v_lshlrev_b32_e32 v178, 2, v178
	s_nop 1
	global_load_dwordx4 v[160:163], v178, s[0:1]
	v_readlane_b32 s0, v215, 38
	v_readlane_b32 s1, v215, 39
	s_mov_b32 vcc_hi, 0x7060302
	s_nop 3
	global_load_dwordx4 v[164:167], v178, s[0:1]
	v_readlane_b32 s20, v214, 20
	s_add_i32 s28, s20, 0x4000
	s_waitcnt vmcnt(0)
	s_lshl_b32 s1, s28, 7
	v_add_u32_e32 v169, s1, v172
	global_load_dwordx4 v[100:103], v169, s[94:95]
	s_mul_i32 s1, s28, 0x3000
	v_add_u32_e32 v169, s1, v177
	global_load_dwordx4 v[104:107], v169, s[94:95]
	s_lshl_b32 s1, s28, 11
	v_add_u32_e32 v169, s1, v174
	global_load_dwordx4 v[108:111], v169, s[94:95]
	s_mul_i32 s1, s28, 0x1900
	v_add_u32_e32 v169, s1, v175
	global_load_dwordx2 v[112:113], v169, s[94:95]
	s_add_i32 s0, s28, 4
	s_lshl_b32 s1, s0, 7
	v_add_u32_e32 v169, s1, v172
	global_load_dwordx4 v[114:117], v169, s[94:95]
	s_mul_i32 s1, s0, 0x3000
	v_add_u32_e32 v169, s1, v177
	global_load_dwordx4 v[118:121], v169, s[94:95]
	s_lshl_b32 s1, s0, 11
	v_add_u32_e32 v169, s1, v174
	global_load_dwordx4 v[122:125], v169, s[94:95]
	s_mul_i32 s1, s0, 0x1900
	v_add_u32_e32 v169, s1, v175
	global_load_dwordx2 v[126:127], v169, s[94:95]
	s_add_i32 s0, s28, 8
	s_lshl_b32 s1, s0, 7
	v_add_u32_e32 v169, s1, v172
	global_load_dwordx4 v[134:137], v169, s[94:95]
	s_mul_i32 s1, s0, 0x3000
	v_add_u32_e32 v169, s1, v177
	global_load_dwordx4 v[138:141], v169, s[94:95]
	s_lshl_b32 s1, s0, 11
	v_add_u32_e32 v169, s1, v174
	global_load_dwordx4 v[142:145], v169, s[94:95]
	s_mul_i32 s1, s0, 0x1900
	v_add_u32_e32 v169, s1, v175
	global_load_dwordx2 v[146:147], v169, s[94:95]
	s_waitcnt vmcnt(8)
	v_fmac_f32_e32 v108, v102, v104
	v_fmac_f32_e32 v109, v102, v105
	v_fmac_f32_e32 v110, v102, v106
	v_fmac_f32_e32 v111, v102, v107
	v_add_f32_e32 v148, v108, v109
	v_add_f32_e32 v149, v110, v111
	v_lshlrev_b32_e32 v150, 16, v112
	v_add_f32_e32 v148, v148, v149
	v_and_b32_e32 v151, 0xffff0000, v112
	v_lshlrev_b32_e32 v152, 16, v113
	v_add_f32_dpp v148, v148, v148 quad_perm:[1,0,3,2] row_mask:0xf bank_mask:0xf bound_ctrl:1
	v_and_b32_e32 v153, 0xffff0000, v113
	v_mul_f32_e32 v154, 0xbfb8aa3b, v150
	v_add_f32_dpp v148, v148, v148 quad_perm:[2,3,0,1] row_mask:0xf bank_mask:0xf bound_ctrl:1
	v_mul_f32_e32 v155, 0xbfb8aa3b, v151
	v_mul_f32_e32 v156, 0xbfb8aa3b, v152
	v_add_f32_dpp v148, v148, v148 row_half_mirror row_mask:0xf bank_mask:0xf bound_ctrl:1
	v_mul_f32_e32 v157, 0xbfb8aa3b, v153
	v_exp_f32_e32 v154, v154
	v_add_f32_dpp v148, v148, v148 row_mirror row_mask:0xf bank_mask:0xf bound_ctrl:1
	v_exp_f32_e32 v155, v155
	v_exp_f32_e32 v156, v156
	v_fmac_f32_e32 v108, v148, v193
	v_fmac_f32_e32 v109, v148, v193
	v_fmac_f32_e32 v110, v148, v193
	v_fmac_f32_e32 v111, v148, v193
	v_exp_f32_e32 v157, v157
	v_mul_f32_e32 v149, v108, v108
	v_fmac_f32_e32 v149, v109, v109
	v_fmac_f32_e32 v149, v110, v110
	v_fmac_f32_e32 v149, v111, v111
	v_add_f32_e32 v154, 1.0, v154
	v_add_f32_e32 v155, 1.0, v155
	v_add_f32_dpp v149, v149, v149 quad_perm:[1,0,3,2] row_mask:0xf bank_mask:0xf bound_ctrl:1
	v_add_f32_e32 v156, 1.0, v156
	v_add_f32_e32 v157, 1.0, v157
	v_add_f32_dpp v149, v149, v149 quad_perm:[2,3,0,1] row_mask:0xf bank_mask:0xf bound_ctrl:1
	v_rcp_f32_e32 v154, v154
	v_rcp_f32_e32 v155, v155
	v_add_f32_dpp v149, v149, v149 row_half_mirror row_mask:0xf bank_mask:0xf bound_ctrl:1
	v_rcp_f32_e32 v156, v156
	v_rcp_f32_e32 v157, v157
	v_add_f32_dpp v149, v149, v149 row_mirror row_mask:0xf bank_mask:0xf bound_ctrl:1
	v_mul_f32_e32 v154, v154, v150
	v_mul_f32_e32 v155, v155, v151
	v_mul_f32_e32 v156, v156, v152
	v_mul_f32_e32 v157, v157, v153
	v_fma_f32 v149, v149, v194, v189
	s_nop 0
	v_rsq_f32_e32 v149, v149
	s_lshl_b32 s1, s28, 11
	v_add_u32_e32 v148, s1, v176
	v_mul_f32_e32 v108, v108, v149
	v_mul_f32_e32 v109, v109, v149
	v_mul_f32_e32 v110, v110, v149
	v_mul_f32_e32 v111, v111, v149
	v_fma_f32 v108, v160, v108, v164
	v_fma_f32 v109, v161, v109, v165
	v_fma_f32 v110, v162, v110, v166
	v_fma_f32 v111, v163, v111, v167
	v_fmac_f32_e32 v108, v100, v104
	v_fmac_f32_e32 v109, v100, v105
	v_fmac_f32_e32 v110, v100, v106
	v_fmac_f32_e32 v111, v100, v107
	v_mul_f32_e32 v108, v108, v154
	v_mul_f32_e32 v109, v109, v155
	v_mul_f32_e32 v110, v110, v156
	v_mul_f32_e32 v111, v111, v157
	v_bfe_u32 v150, v108, 16, 1
	v_bfe_u32 v151, v109, 16, 1
	v_bfe_u32 v152, v110, 16, 1
	v_bfe_u32 v153, v111, 16, 1
	v_add3_u32 v108, v108, v150, s27
	v_add3_u32 v109, v109, v151, s27
	v_add3_u32 v110, v110, v152, s27
	v_add3_u32 v111, v111, v153, s27
	v_perm_b32 v150, v109, v108, vcc_hi
	v_perm_b32 v151, v111, v110, vcc_hi
	s_nop 0
	global_store_dwordx2 v148, v[150:151], s[94:95]
	s_add_i32 s0, s28, 12
	s_lshl_b32 s1, s0, 7
	v_add_u32_e32 v169, s1, v172
	global_load_dwordx4 v[100:103], v169, s[94:95]
	s_mul_i32 s1, s0, 0x3000
	v_add_u32_e32 v169, s1, v177
	global_load_dwordx4 v[104:107], v169, s[94:95]
	s_lshl_b32 s1, s0, 11
	v_add_u32_e32 v169, s1, v174
	global_load_dwordx4 v[108:111], v169, s[94:95]
	s_mul_i32 s1, s0, 0x1900
	v_add_u32_e32 v169, s1, v175
	global_load_dwordx2 v[112:113], v169, s[94:95]
	s_waitcnt vmcnt(8)
	v_fmac_f32_e32 v122, v116, v118
	v_fmac_f32_e32 v123, v116, v119
	v_fmac_f32_e32 v124, v116, v120
	v_fmac_f32_e32 v125, v116, v121
	v_add_f32_e32 v148, v122, v123
	v_add_f32_e32 v149, v124, v125
	v_lshlrev_b32_e32 v150, 16, v126
	v_add_f32_e32 v148, v148, v149
	v_and_b32_e32 v151, 0xffff0000, v126
	v_lshlrev_b32_e32 v152, 16, v127
	v_add_f32_dpp v148, v148, v148 quad_perm:[1,0,3,2] row_mask:0xf bank_mask:0xf bound_ctrl:1
	v_and_b32_e32 v153, 0xffff0000, v127
	v_mul_f32_e32 v154, 0xbfb8aa3b, v150
	v_add_f32_dpp v148, v148, v148 quad_perm:[2,3,0,1] row_mask:0xf bank_mask:0xf bound_ctrl:1
	v_mul_f32_e32 v155, 0xbfb8aa3b, v151
	v_mul_f32_e32 v156, 0xbfb8aa3b, v152
	v_add_f32_dpp v148, v148, v148 row_half_mirror row_mask:0xf bank_mask:0xf bound_ctrl:1
	v_mul_f32_e32 v157, 0xbfb8aa3b, v153
	v_exp_f32_e32 v154, v154
	v_add_f32_dpp v148, v148, v148 row_mirror row_mask:0xf bank_mask:0xf bound_ctrl:1
	v_exp_f32_e32 v155, v155
	v_exp_f32_e32 v156, v156
	v_fmac_f32_e32 v122, v148, v193
	v_fmac_f32_e32 v123, v148, v193
	v_fmac_f32_e32 v124, v148, v193
	v_fmac_f32_e32 v125, v148, v193
	v_exp_f32_e32 v157, v157
	v_mul_f32_e32 v149, v122, v122
	v_fmac_f32_e32 v149, v123, v123
	v_fmac_f32_e32 v149, v124, v124
	v_fmac_f32_e32 v149, v125, v125
	v_add_f32_e32 v154, 1.0, v154
	v_add_f32_e32 v155, 1.0, v155
	v_add_f32_dpp v149, v149, v149 quad_perm:[1,0,3,2] row_mask:0xf bank_mask:0xf bound_ctrl:1
	v_add_f32_e32 v156, 1.0, v156
	v_add_f32_e32 v157, 1.0, v157
	v_add_f32_dpp v149, v149, v149 quad_perm:[2,3,0,1] row_mask:0xf bank_mask:0xf bound_ctrl:1
	v_rcp_f32_e32 v154, v154
	v_rcp_f32_e32 v155, v155
	v_add_f32_dpp v149, v149, v149 row_half_mirror row_mask:0xf bank_mask:0xf bound_ctrl:1
	v_rcp_f32_e32 v156, v156
	v_rcp_f32_e32 v157, v157
	v_add_f32_dpp v149, v149, v149 row_mirror row_mask:0xf bank_mask:0xf bound_ctrl:1
	v_mul_f32_e32 v154, v154, v150
	v_mul_f32_e32 v155, v155, v151
	v_mul_f32_e32 v156, v156, v152
	v_mul_f32_e32 v157, v157, v153
	v_fma_f32 v149, v149, v194, v189
	s_nop 0
	v_rsq_f32_e32 v149, v149
	s_add_i32 s0, s28, 4
	s_lshl_b32 s1, s0, 11
	v_add_u32_e32 v148, s1, v176
	v_mul_f32_e32 v122, v122, v149
	v_mul_f32_e32 v123, v123, v149
	v_mul_f32_e32 v124, v124, v149
	v_mul_f32_e32 v125, v125, v149
	v_fma_f32 v122, v160, v122, v164
	v_fma_f32 v123, v161, v123, v165
	v_fma_f32 v124, v162, v124, v166
	v_fma_f32 v125, v163, v125, v167
	v_fmac_f32_e32 v122, v114, v118
	v_fmac_f32_e32 v123, v114, v119
	v_fmac_f32_e32 v124, v114, v120
	v_fmac_f32_e32 v125, v114, v121
	v_mul_f32_e32 v122, v122, v154
	v_mul_f32_e32 v123, v123, v155
	v_mul_f32_e32 v124, v124, v156
	v_mul_f32_e32 v125, v125, v157
	v_bfe_u32 v150, v122, 16, 1
	v_bfe_u32 v151, v123, 16, 1
	v_bfe_u32 v152, v124, 16, 1
	v_bfe_u32 v153, v125, 16, 1
	v_add3_u32 v122, v122, v150, s27
	v_add3_u32 v123, v123, v151, s27
	v_add3_u32 v124, v124, v152, s27
	v_add3_u32 v125, v125, v153, s27
	v_perm_b32 v150, v123, v122, vcc_hi
	v_perm_b32 v151, v125, v124, vcc_hi
	s_nop 0
	global_store_dwordx2 v148, v[150:151], s[94:95]
	s_waitcnt vmcnt(4)
	v_fmac_f32_e32 v142, v136, v138
	v_fmac_f32_e32 v143, v136, v139
	v_fmac_f32_e32 v144, v136, v140
	v_fmac_f32_e32 v145, v136, v141
	v_add_f32_e32 v148, v142, v143
	v_add_f32_e32 v149, v144, v145
	v_lshlrev_b32_e32 v150, 16, v146
	v_add_f32_e32 v148, v148, v149
	v_and_b32_e32 v151, 0xffff0000, v146
	v_lshlrev_b32_e32 v152, 16, v147
	v_add_f32_dpp v148, v148, v148 quad_perm:[1,0,3,2] row_mask:0xf bank_mask:0xf bound_ctrl:1
	v_and_b32_e32 v153, 0xffff0000, v147
	v_mul_f32_e32 v154, 0xbfb8aa3b, v150
	v_add_f32_dpp v148, v148, v148 quad_perm:[2,3,0,1] row_mask:0xf bank_mask:0xf bound_ctrl:1
	v_mul_f32_e32 v155, 0xbfb8aa3b, v151
	v_mul_f32_e32 v156, 0xbfb8aa3b, v152
	v_add_f32_dpp v148, v148, v148 row_half_mirror row_mask:0xf bank_mask:0xf bound_ctrl:1
	v_mul_f32_e32 v157, 0xbfb8aa3b, v153
	v_exp_f32_e32 v154, v154
	v_add_f32_dpp v148, v148, v148 row_mirror row_mask:0xf bank_mask:0xf bound_ctrl:1
	v_exp_f32_e32 v155, v155
	v_exp_f32_e32 v156, v156
	v_fmac_f32_e32 v142, v148, v193
	v_fmac_f32_e32 v143, v148, v193
	v_fmac_f32_e32 v144, v148, v193
	v_fmac_f32_e32 v145, v148, v193
	v_exp_f32_e32 v157, v157
	v_mul_f32_e32 v149, v142, v142
	v_fmac_f32_e32 v149, v143, v143
	v_fmac_f32_e32 v149, v144, v144
	v_fmac_f32_e32 v149, v145, v145
	v_add_f32_e32 v154, 1.0, v154
	v_add_f32_e32 v155, 1.0, v155
	v_add_f32_dpp v149, v149, v149 quad_perm:[1,0,3,2] row_mask:0xf bank_mask:0xf bound_ctrl:1
	v_add_f32_e32 v156, 1.0, v156
	v_add_f32_e32 v157, 1.0, v157
	v_add_f32_dpp v149, v149, v149 quad_perm:[2,3,0,1] row_mask:0xf bank_mask:0xf bound_ctrl:1
	v_rcp_f32_e32 v154, v154
	v_rcp_f32_e32 v155, v155
	v_add_f32_dpp v149, v149, v149 row_half_mirror row_mask:0xf bank_mask:0xf bound_ctrl:1
	v_rcp_f32_e32 v156, v156
	v_rcp_f32_e32 v157, v157
	v_add_f32_dpp v149, v149, v149 row_mirror row_mask:0xf bank_mask:0xf bound_ctrl:1
	v_mul_f32_e32 v154, v154, v150
	v_mul_f32_e32 v155, v155, v151
	v_mul_f32_e32 v156, v156, v152
	v_mul_f32_e32 v157, v157, v153
	v_fma_f32 v149, v149, v194, v189
	s_nop 0
	v_rsq_f32_e32 v149, v149
	s_add_i32 s0, s28, 8
	s_lshl_b32 s1, s0, 11
	v_add_u32_e32 v148, s1, v176
	v_mul_f32_e32 v142, v142, v149
	v_mul_f32_e32 v143, v143, v149
	v_mul_f32_e32 v144, v144, v149
	v_mul_f32_e32 v145, v145, v149
	v_fma_f32 v142, v160, v142, v164
	v_fma_f32 v143, v161, v143, v165
	v_fma_f32 v144, v162, v144, v166
	v_fma_f32 v145, v163, v145, v167
	v_fmac_f32_e32 v142, v134, v138
	v_fmac_f32_e32 v143, v134, v139
	v_fmac_f32_e32 v144, v134, v140
	v_fmac_f32_e32 v145, v134, v141
	v_mul_f32_e32 v142, v142, v154
	v_mul_f32_e32 v143, v143, v155
	v_mul_f32_e32 v144, v144, v156
	v_mul_f32_e32 v145, v145, v157
	v_bfe_u32 v150, v142, 16, 1
	v_bfe_u32 v151, v143, 16, 1
	v_bfe_u32 v152, v144, 16, 1
	v_bfe_u32 v153, v145, 16, 1
	v_add3_u32 v142, v142, v150, s27
	v_add3_u32 v143, v143, v151, s27
	v_add3_u32 v144, v144, v152, s27
	v_add3_u32 v145, v145, v153, s27
	v_perm_b32 v150, v143, v142, vcc_hi
	v_perm_b32 v151, v145, v144, vcc_hi
	s_nop 0
	global_store_dwordx2 v148, v[150:151], s[94:95]
	s_waitcnt vmcnt(0)
	v_fmac_f32_e32 v108, v102, v104
	v_fmac_f32_e32 v109, v102, v105
	v_fmac_f32_e32 v110, v102, v106
	v_fmac_f32_e32 v111, v102, v107
	v_add_f32_e32 v148, v108, v109
	v_add_f32_e32 v149, v110, v111
	v_lshlrev_b32_e32 v150, 16, v112
	v_add_f32_e32 v148, v148, v149
	v_and_b32_e32 v151, 0xffff0000, v112
	v_lshlrev_b32_e32 v152, 16, v113
	v_add_f32_dpp v148, v148, v148 quad_perm:[1,0,3,2] row_mask:0xf bank_mask:0xf bound_ctrl:1
	v_and_b32_e32 v153, 0xffff0000, v113
	v_mul_f32_e32 v154, 0xbfb8aa3b, v150
	v_add_f32_dpp v148, v148, v148 quad_perm:[2,3,0,1] row_mask:0xf bank_mask:0xf bound_ctrl:1
	v_mul_f32_e32 v155, 0xbfb8aa3b, v151
	v_mul_f32_e32 v156, 0xbfb8aa3b, v152
	v_add_f32_dpp v148, v148, v148 row_half_mirror row_mask:0xf bank_mask:0xf bound_ctrl:1
	v_mul_f32_e32 v157, 0xbfb8aa3b, v153
	v_exp_f32_e32 v154, v154
	v_add_f32_dpp v148, v148, v148 row_mirror row_mask:0xf bank_mask:0xf bound_ctrl:1
	v_exp_f32_e32 v155, v155
	v_exp_f32_e32 v156, v156
	v_fmac_f32_e32 v108, v148, v193
	v_fmac_f32_e32 v109, v148, v193
	v_fmac_f32_e32 v110, v148, v193
	v_fmac_f32_e32 v111, v148, v193
	v_exp_f32_e32 v157, v157
	v_mul_f32_e32 v149, v108, v108
	v_fmac_f32_e32 v149, v109, v109
	v_fmac_f32_e32 v149, v110, v110
	v_fmac_f32_e32 v149, v111, v111
	v_add_f32_e32 v154, 1.0, v154
	v_add_f32_e32 v155, 1.0, v155
	v_add_f32_dpp v149, v149, v149 quad_perm:[1,0,3,2] row_mask:0xf bank_mask:0xf bound_ctrl:1
	v_add_f32_e32 v156, 1.0, v156
	v_add_f32_e32 v157, 1.0, v157
	v_add_f32_dpp v149, v149, v149 quad_perm:[2,3,0,1] row_mask:0xf bank_mask:0xf bound_ctrl:1
	v_rcp_f32_e32 v154, v154
	v_rcp_f32_e32 v155, v155
	v_add_f32_dpp v149, v149, v149 row_half_mirror row_mask:0xf bank_mask:0xf bound_ctrl:1
	v_rcp_f32_e32 v156, v156
	v_rcp_f32_e32 v157, v157
	v_add_f32_dpp v149, v149, v149 row_mirror row_mask:0xf bank_mask:0xf bound_ctrl:1
	v_mul_f32_e32 v154, v154, v150
	v_mul_f32_e32 v155, v155, v151
	v_mul_f32_e32 v156, v156, v152
	v_mul_f32_e32 v157, v157, v153
	v_fma_f32 v149, v149, v194, v189
	s_nop 0
	v_rsq_f32_e32 v149, v149
	s_add_i32 s0, s28, 12
	s_lshl_b32 s1, s0, 11
	v_add_u32_e32 v148, s1, v176
	v_mul_f32_e32 v108, v108, v149
	v_mul_f32_e32 v109, v109, v149
	v_mul_f32_e32 v110, v110, v149
	v_mul_f32_e32 v111, v111, v149
	v_fma_f32 v108, v160, v108, v164
	v_fma_f32 v109, v161, v109, v165
	v_fma_f32 v110, v162, v110, v166
	v_fma_f32 v111, v163, v111, v167
	v_fmac_f32_e32 v108, v100, v104
	v_fmac_f32_e32 v109, v100, v105
	v_fmac_f32_e32 v110, v100, v106
	v_fmac_f32_e32 v111, v100, v107
	v_mul_f32_e32 v108, v108, v154
	v_mul_f32_e32 v109, v109, v155
	v_mul_f32_e32 v110, v110, v156
	v_mul_f32_e32 v111, v111, v157
	v_bfe_u32 v150, v108, 16, 1
	v_bfe_u32 v151, v109, 16, 1
	v_bfe_u32 v152, v110, 16, 1
	v_bfe_u32 v153, v111, 16, 1
	v_add3_u32 v108, v108, v150, s27
	v_add3_u32 v109, v109, v151, s27
	v_add3_u32 v110, v110, v152, s27
	v_add3_u32 v111, v111, v153, s27
	v_perm_b32 v150, v109, v108, vcc_hi
	v_perm_b32 v151, v111, v110, vcc_hi
	s_nop 0
	global_store_dwordx2 v148, v[150:151], s[94:95]
	s_branch .LBB0_227
